# v36 + GEMM unit prologues zero the 128 accumulators with 63 v_mov_b64 instead of 127 v_mov_b32 (prologue trimming)
# speedup vs baseline: 1.0024x; 1.0024x over previous
; template <class Epi, class Sched, bool ALIGN_EPI>
; __device__ __forceinline__ void gemm_phase(LAS unsigned char* lds, const Gemm g, const Sched& S, const Epi& E) {
;     ...
;         const bool has_next = S.next(ui + 1, nxt);
;         const char* nA = has_next ? (const char*)g.A + (size_t)nxt.pm * tstepA + (size_t)nxt.pn * g.a_koff * 2 : cA; const char* nB = has_next ? (const char*)g.Bt + (size_t)nxt.pn * tstepB : cB;
; #pragma unroll 1
;         for (int t = 0; t < nt; t += 2) {
;             const bool last = (t == nt - 2);
;             const char* a1 = cA + (size_t)(t + 1) * kstep;
;             const char* a2 = last ? nA : cA + (size_t)(t + 2) * kstep; const char* b2 = last ? nB : cB + (size_t)(t + 2) * kstep;
;             const char* a3 = a2 + kstep; const char* b3 = b2 + kstep;
;             PG8_LDB(B0, 0, 0); PG8_LDB(B1, 0, 1); PG8_SCHED; PG8_LDA(At, 0, 0); PG8_STAGE(PG8_SA(1, 1), a1 + hstepA, voffA);
;             PG8_WAIT_V(8); PG8_WAIT_L(0); PG8_BAR; PG8_MMA(0, 0, At, B0); PG8_MMA(0, 1, At, B1); PG8_BAR; PG8_SCHED;
;             PG8_LDA(At, 0, 1); PG8_STAGE(PG8_SB(0, 0), b2, voffB); PG8_STAGE(PG8_SB(0, 1), b2 + hstepB, voffB); PG8_STAGE(PG8_SA(0, 0), a2, voffA);
;             PG8_WAIT_V(8); PG8_WAIT_L(0); PG8_BAR; PG8_MMA(1, 0, At, B0); PG8_MMA(1, 1, At, B1); PG8_BAR; PG8_SCHED;
;             PG8_LDB(B0, 1, 0); PG8_LDB(B1, 1, 1); PG8_SCHED; PG8_LDA(At, 1, 0); PG8_STAGE(PG8_SA(0, 1), a2 + hstepA, voffA);
;             PG8_WAIT_V(8); PG8_WAIT_L(0); PG8_BAR; PG8_MMA(0, 0, At, B0); PG8_MMA(0, 1, At, B1); PG8_BAR; PG8_SCHED;
;             PG8_LDA(At, 1, 1); PG8_STAGE(PG8_SB(1, 0), b3, voffB); PG8_STAGE(PG8_SB(1, 1), b3 + hstepB, voffB); PG8_STAGE(PG8_SA(1, 0), a3, voffA);
;             PG8_WAIT_V(8); PG8_WAIT_L(0); PG8_BAR; PG8_MMA(1, 0, At, B0); PG8_MMA(1, 1, At, B1); PG8_BAR; PG8_SCHED;
;         }
;         if constexpr (ALIGN_EPI) { if (wr == 0) PG8_BAR; }
;         if constexpr (Epi::NPRE > 0) E(acc, cur, wr, wc, fr, fq, pre); else
;         if constexpr (!Epi::AFTER_DRAIN) E(acc, cur, wr, wc, fr, fq);
;         if (!has_next) break;
; #pragma unroll
;         for (int a = 0; a < 2; ++a)
; #pragma unroll
;             for (int b = 0; b < 2; ++b)
; #pragma unroll
;                 for (int m = 0; m < 4; ++m)
; #pragma unroll
;                     for (int n = 0; n < 2; ++n) acc[a][b][m][n] = (f32x4){0.f, 0.f, 0.f, 0.f};
.LBB0_112:
	s_mov_b32 s38, s41
	s_mov_b32 s40, s39
	s_ashr_i32 s39, s41, 31
	s_lshl_b64 s[8:9], s[38:39], 20
	s_add_u32 s42, s53, s8
	s_addc_u32 s43, s54, s9
	s_and_b64 s[8:9], s[46:47], exec
	s_cselect_b32 s24, s43, s5
	s_cselect_b32 s39, s42, s4
	s_ashr_i32 s41, s40, 31
	s_lshl_b64 s[8:9], s[40:41], 20
	s_add_u32 s44, s55, s8
	s_addc_u32 s45, s57, s9
	s_and_b64 s[8:9], s[46:47], exec
	s_cselect_b32 s41, s45, s7
	s_cselect_b32 s58, s44, s6
	s_add_u32 s59, s6, 0x100
	v_mov_b32_e32 v2, 0
	s_addc_u32 s80, s7, 0
	s_mov_b32 s81, -2
	v_mov_b32_e32 v3, v2
	v_mov_b64_e32 v[4:5], 0
	v_mov_b64_e32 v[6:7], 0
	v_mov_b64_e32 v[8:9], 0
	v_mov_b64_e32 v[10:11], 0
	v_mov_b64_e32 v[12:13], 0
	v_mov_b64_e32 v[14:15], 0
	v_mov_b64_e32 v[16:17], 0
	v_mov_b64_e32 v[18:19], 0
	v_mov_b64_e32 v[20:21], 0
	v_mov_b64_e32 v[22:23], 0
	v_mov_b64_e32 v[24:25], 0
	v_mov_b64_e32 v[26:27], 0
	v_mov_b64_e32 v[28:29], 0
	v_mov_b64_e32 v[30:31], 0
	v_mov_b64_e32 v[32:33], 0
	v_mov_b64_e32 v[34:35], 0
	v_mov_b64_e32 v[36:37], 0
	v_mov_b64_e32 v[38:39], 0
	v_mov_b64_e32 v[40:41], 0
	v_mov_b64_e32 v[42:43], 0
	v_mov_b64_e32 v[44:45], 0
	v_mov_b64_e32 v[46:47], 0
	v_mov_b64_e32 v[48:49], 0
	v_mov_b64_e32 v[50:51], 0
	v_mov_b64_e32 v[52:53], 0
	v_mov_b64_e32 v[54:55], 0
	v_mov_b64_e32 v[56:57], 0
	v_mov_b64_e32 v[58:59], 0
	v_mov_b64_e32 v[60:61], 0
	v_mov_b64_e32 v[62:63], 0
	v_mov_b64_e32 v[64:65], 0
	v_mov_b64_e32 v[66:67], 0
	v_mov_b64_e32 v[68:69], 0
	v_mov_b64_e32 v[70:71], 0
	v_mov_b64_e32 v[72:73], 0
	v_mov_b64_e32 v[74:75], 0
	v_mov_b64_e32 v[76:77], 0
	v_mov_b64_e32 v[78:79], 0
	v_mov_b64_e32 v[80:81], 0
	v_mov_b64_e32 v[82:83], 0
	v_mov_b64_e32 v[84:85], 0
	v_mov_b64_e32 v[86:87], 0
	v_mov_b64_e32 v[88:89], 0
	v_mov_b64_e32 v[90:91], 0
	v_mov_b64_e32 v[92:93], 0
	v_mov_b64_e32 v[94:95], 0
	v_mov_b64_e32 v[96:97], 0
	v_mov_b64_e32 v[98:99], 0
	v_mov_b64_e32 v[100:101], 0
	v_mov_b64_e32 v[102:103], 0
	v_mov_b64_e32 v[104:105], 0
	v_mov_b64_e32 v[106:107], 0
	v_mov_b64_e32 v[108:109], 0
	v_mov_b64_e32 v[110:111], 0
	v_mov_b64_e32 v[112:113], 0
	v_mov_b64_e32 v[114:115], 0
	v_mov_b64_e32 v[116:117], 0
	v_mov_b64_e32 v[118:119], 0
	v_mov_b64_e32 v[120:121], 0
	v_mov_b64_e32 v[122:123], 0
	v_mov_b64_e32 v[124:125], 0
	v_mov_b64_e32 v[126:127], 0
	v_mov_b64_e32 v[128:129], 0

; template <class Epi, class Sched, bool ALIGN_EPI>
; __device__ __forceinline__ void gemm_phase(LAS unsigned char* lds, const Gemm g, const Sched& S, const Epi& E) {
;     ...
;         const bool has_next = S.next(ui + 1, nxt);
;         const char* nA = has_next ? (const char*)g.A + (size_t)nxt.pm * tstepA + (size_t)nxt.pn * g.a_koff * 2 : cA; const char* nB = has_next ? (const char*)g.Bt + (size_t)nxt.pn * tstepB : cB;
; #pragma unroll 1
;         for (int t = 0; t < nt; t += 2) {
;             const bool last = (t == nt - 2);
;             const char* a1 = cA + (size_t)(t + 1) * kstep;
;             const char* a2 = last ? nA : cA + (size_t)(t + 2) * kstep; const char* b2 = last ? nB : cB + (size_t)(t + 2) * kstep;
;             const char* a3 = a2 + kstep; const char* b3 = b2 + kstep;
;             PG8_LDB(B0, 0, 0); PG8_LDB(B1, 0, 1); PG8_SCHED; PG8_LDA(At, 0, 0); PG8_STAGE(PG8_SA(1, 1), a1 + hstepA, voffA);
;             PG8_WAIT_V(8); PG8_WAIT_L(0); PG8_BAR; PG8_MMA(0, 0, At, B0); PG8_MMA(0, 1, At, B1); PG8_BAR; PG8_SCHED;
;             PG8_LDA(At, 0, 1); PG8_STAGE(PG8_SB(0, 0), b2, voffB); PG8_STAGE(PG8_SB(0, 1), b2 + hstepB, voffB); PG8_STAGE(PG8_SA(0, 0), a2, voffA);
;             PG8_WAIT_V(8); PG8_WAIT_L(0); PG8_BAR; PG8_MMA(1, 0, At, B0); PG8_MMA(1, 1, At, B1); PG8_BAR; PG8_SCHED;
;             PG8_LDB(B0, 1, 0); PG8_LDB(B1, 1, 1); PG8_SCHED; PG8_LDA(At, 1, 0); PG8_STAGE(PG8_SA(0, 1), a2 + hstepA, voffA);
;             PG8_WAIT_V(8); PG8_WAIT_L(0); PG8_BAR; PG8_MMA(0, 0, At, B0); PG8_MMA(0, 1, At, B1); PG8_BAR; PG8_SCHED;
;             PG8_LDA(At, 1, 1); PG8_STAGE(PG8_SB(1, 0), b3, voffB); PG8_STAGE(PG8_SB(1, 1), b3 + hstepB, voffB); PG8_STAGE(PG8_SA(1, 0), a3, voffA);
;             PG8_WAIT_V(8); PG8_WAIT_L(0); PG8_BAR; PG8_MMA(1, 0, At, B0); PG8_MMA(1, 1, At, B1); PG8_BAR; PG8_SCHED;
;         }
;         if constexpr (ALIGN_EPI) { if (wr == 0) PG8_BAR; }
;         if constexpr (Epi::NPRE > 0) E(acc, cur, wr, wc, fr, fq, pre); else
;         if constexpr (!Epi::AFTER_DRAIN) E(acc, cur, wr, wc, fr, fq);
;         if (!has_next) break;
; #pragma unroll
;         for (int a = 0; a < 2; ++a)
; #pragma unroll
;             for (int b = 0; b < 2; ++b)
; #pragma unroll
;                 for (int m = 0; m < 4; ++m)
; #pragma unroll
;                     for (int n = 0; n < 2; ++n) acc[a][b][m][n] = (f32x4){0.f, 0.f, 0.f, 0.f};
.LBB0_804:
	s_ashr_i32 s17, s16, 31
	s_lshl_b64 s[18:19], s[16:17], 19
	s_add_u32 s3, s23, s18
	s_addc_u32 s17, s24, s19
	s_ashr_i32 s15, s14, 31
	s_lshl_b64 s[18:19], s[14:15], 9
	s_add_u32 s18, s3, s18
	s_addc_u32 s19, s17, s19
	s_and_b64 s[26:27], s[6:7], exec
	s_cselect_b32 s3, s19, s35
	s_cselect_b32 s17, s18, s34
	s_lshl_b64 s[26:27], s[14:15], 17
	s_add_u32 s26, s25, s26
	s_addc_u32 s27, s54, s27
	s_and_b64 s[36:37], s[6:7], exec
	v_mov_b32_e32 v2, 0
	s_cselect_b32 s15, s27, s31
	s_cselect_b32 s72, s26, s30
	s_mov_b64 s[40:41], 0
	s_mov_b64 s[36:37], -1
	s_mov_b64 s[38:39], 0
	v_mov_b32_e32 v3, v2
	v_mov_b64_e32 v[4:5], 0
	v_mov_b64_e32 v[6:7], 0
	v_mov_b64_e32 v[8:9], 0
	v_mov_b64_e32 v[10:11], 0
	v_mov_b64_e32 v[12:13], 0
	v_mov_b64_e32 v[14:15], 0
	v_mov_b64_e32 v[16:17], 0
	v_mov_b64_e32 v[18:19], 0
	v_mov_b64_e32 v[20:21], 0
	v_mov_b64_e32 v[22:23], 0
	v_mov_b64_e32 v[24:25], 0
	v_mov_b64_e32 v[26:27], 0
	v_mov_b64_e32 v[28:29], 0
	v_mov_b64_e32 v[30:31], 0
	v_mov_b64_e32 v[32:33], 0
	v_mov_b64_e32 v[34:35], 0
	v_mov_b64_e32 v[36:37], 0
	v_mov_b64_e32 v[38:39], 0
	v_mov_b64_e32 v[40:41], 0
	v_mov_b64_e32 v[42:43], 0
	v_mov_b64_e32 v[44:45], 0
	v_mov_b64_e32 v[46:47], 0
	v_mov_b64_e32 v[48:49], 0
	v_mov_b64_e32 v[50:51], 0
	v_mov_b64_e32 v[52:53], 0
	v_mov_b64_e32 v[54:55], 0
	v_mov_b64_e32 v[56:57], 0
	v_mov_b64_e32 v[58:59], 0
	v_mov_b64_e32 v[60:61], 0
	v_mov_b64_e32 v[62:63], 0
	v_mov_b64_e32 v[64:65], 0
	v_mov_b64_e32 v[66:67], 0
	v_mov_b64_e32 v[68:69], 0
	v_mov_b64_e32 v[70:71], 0
	v_mov_b64_e32 v[72:73], 0
	v_mov_b64_e32 v[74:75], 0
	v_mov_b64_e32 v[76:77], 0
	v_mov_b64_e32 v[78:79], 0
	v_mov_b64_e32 v[80:81], 0
	v_mov_b64_e32 v[82:83], 0
	v_mov_b64_e32 v[84:85], 0
	v_mov_b64_e32 v[86:87], 0
	v_mov_b64_e32 v[88:89], 0
	v_mov_b64_e32 v[90:91], 0
	v_mov_b64_e32 v[92:93], 0
	v_mov_b64_e32 v[94:95], 0
	v_mov_b64_e32 v[96:97], 0
	v_mov_b64_e32 v[98:99], 0
	v_mov_b64_e32 v[100:101], 0
	v_mov_b64_e32 v[102:103], 0
	v_mov_b64_e32 v[104:105], 0
	v_mov_b64_e32 v[106:107], 0
	v_mov_b64_e32 v[108:109], 0
	v_mov_b64_e32 v[110:111], 0
	v_mov_b64_e32 v[112:113], 0
	v_mov_b64_e32 v[114:115], 0
	v_mov_b64_e32 v[116:117], 0
	v_mov_b64_e32 v[118:119], 0
	v_mov_b64_e32 v[120:121], 0
	v_mov_b64_e32 v[122:123], 0
	v_mov_b64_e32 v[124:125], 0
	v_mov_b64_e32 v[126:127], 0
	v_mov_b64_e32 v[128:129], 0

; template <class Epi, class Sched, bool ALIGN_EPI>
; __device__ __forceinline__ void gemm_phase(LAS unsigned char* lds, const Gemm g, const Sched& S, const Epi& E) {
;     ...
;         const bool has_next = S.next(ui + 1, nxt);
;         const char* nA = has_next ? (const char*)g.A + (size_t)nxt.pm * tstepA + (size_t)nxt.pn * g.a_koff * 2 : cA; const char* nB = has_next ? (const char*)g.Bt + (size_t)nxt.pn * tstepB : cB;
; #pragma unroll 1
;         for (int t = 0; t < nt; t += 2) {
;             const bool last = (t == nt - 2);
;             const char* a1 = cA + (size_t)(t + 1) * kstep;
;             const char* a2 = last ? nA : cA + (size_t)(t + 2) * kstep; const char* b2 = last ? nB : cB + (size_t)(t + 2) * kstep;
;             const char* a3 = a2 + kstep; const char* b3 = b2 + kstep;
;             PG8_LDB(B0, 0, 0); PG8_LDB(B1, 0, 1); PG8_SCHED; PG8_LDA(At, 0, 0); PG8_STAGE(PG8_SA(1, 1), a1 + hstepA, voffA);
;             PG8_WAIT_V(8); PG8_WAIT_L(0); PG8_BAR; PG8_MMA(0, 0, At, B0); PG8_MMA(0, 1, At, B1); PG8_BAR; PG8_SCHED;
;             PG8_LDA(At, 0, 1); PG8_STAGE(PG8_SB(0, 0), b2, voffB); PG8_STAGE(PG8_SB(0, 1), b2 + hstepB, voffB); PG8_STAGE(PG8_SA(0, 0), a2, voffA);
;             PG8_WAIT_V(8); PG8_WAIT_L(0); PG8_BAR; PG8_MMA(1, 0, At, B0); PG8_MMA(1, 1, At, B1); PG8_BAR; PG8_SCHED;
;             PG8_LDB(B0, 1, 0); PG8_LDB(B1, 1, 1); PG8_SCHED; PG8_LDA(At, 1, 0); PG8_STAGE(PG8_SA(0, 1), a2 + hstepA, voffA);
;             PG8_WAIT_V(8); PG8_WAIT_L(0); PG8_BAR; PG8_MMA(0, 0, At, B0); PG8_MMA(0, 1, At, B1); PG8_BAR; PG8_SCHED;
;             PG8_LDA(At, 1, 1); PG8_STAGE(PG8_SB(1, 0), b3, voffB); PG8_STAGE(PG8_SB(1, 1), b3 + hstepB, voffB); PG8_STAGE(PG8_SA(1, 0), a3, voffA);
;             PG8_WAIT_V(8); PG8_WAIT_L(0); PG8_BAR; PG8_MMA(1, 0, At, B0); PG8_MMA(1, 1, At, B1); PG8_BAR; PG8_SCHED;
;         }
;         if constexpr (ALIGN_EPI) { if (wr == 0) PG8_BAR; }
;         if constexpr (Epi::NPRE > 0) E(acc, cur, wr, wc, fr, fq, pre); else
;         if constexpr (!Epi::AFTER_DRAIN) E(acc, cur, wr, wc, fr, fq);
;         if (!has_next) break;
; #pragma unroll
;         for (int a = 0; a < 2; ++a)
; #pragma unroll
;             for (int b = 0; b < 2; ++b)
; #pragma unroll
;                 for (int m = 0; m < 4; ++m)
; #pragma unroll
;                     for (int n = 0; n < 2; ++n) acc[a][b][m][n] = (f32x4){0.f, 0.f, 0.f, 0.f};
.LBB0_1136:
	s_ashr_i32 s27, s26, 31
	s_lshl_b64 s[6:7], s[26:27], 20
	s_add_u32 s28, s23, s6
	s_addc_u32 s29, s24, s7
	s_and_b64 s[6:7], s[12:13], exec
	s_cselect_b32 s3, s29, s37
	s_cselect_b32 s5, s28, s36
	s_ashr_i32 s19, s18, 31
	s_lshl_b64 s[6:7], s[18:19], 20
	s_add_u32 s30, s25, s6
	s_addc_u32 s31, s42, s7
	s_and_b64 s[6:7], s[12:13], exec
	s_cselect_b32 s6, s31, s35
	s_cselect_b32 s7, s30, s34
	s_add_u32 s19, s36, 0x100
	s_addc_u32 s27, s37, 0
	s_add_u32 s61, s34, 0x100
	s_addc_u32 s62, s35, 0
	s_add_u32 s34, s36, 0x80080
	v_mov_b32_e32 v2, 0
	s_addc_u32 s35, s37, 0
	s_mov_b32 s63, -2
	s_waitcnt lgkmcnt(0)
	v_mov_b32_e32 v3, v2
	v_mov_b64_e32 v[4:5], 0
	v_mov_b64_e32 v[6:7], 0
	v_mov_b64_e32 v[8:9], 0
	v_mov_b64_e32 v[10:11], 0
	v_mov_b64_e32 v[12:13], 0
	v_mov_b64_e32 v[14:15], 0
	v_mov_b64_e32 v[16:17], 0
	v_mov_b64_e32 v[18:19], 0
	v_mov_b64_e32 v[20:21], 0
	v_mov_b64_e32 v[22:23], 0
	v_mov_b64_e32 v[24:25], 0
	v_mov_b64_e32 v[26:27], 0
	v_mov_b64_e32 v[28:29], 0
	v_mov_b64_e32 v[30:31], 0
	v_mov_b64_e32 v[32:33], 0
	v_mov_b64_e32 v[34:35], 0
	v_mov_b64_e32 v[36:37], 0
	v_mov_b64_e32 v[38:39], 0
	v_mov_b64_e32 v[40:41], 0
	v_mov_b64_e32 v[42:43], 0
	v_mov_b64_e32 v[44:45], 0
	v_mov_b64_e32 v[46:47], 0
	v_mov_b64_e32 v[48:49], 0
	v_mov_b64_e32 v[50:51], 0
	v_mov_b64_e32 v[52:53], 0
	v_mov_b64_e32 v[54:55], 0
	v_mov_b64_e32 v[56:57], 0
	v_mov_b64_e32 v[58:59], 0
	v_mov_b64_e32 v[60:61], 0
	v_mov_b64_e32 v[62:63], 0
	v_mov_b64_e32 v[64:65], 0
	v_mov_b64_e32 v[66:67], 0
	v_mov_b64_e32 v[68:69], 0
	v_mov_b64_e32 v[70:71], 0
	v_mov_b64_e32 v[72:73], 0
	v_mov_b64_e32 v[74:75], 0
	v_mov_b64_e32 v[76:77], 0
	v_mov_b64_e32 v[78:79], 0
	v_mov_b64_e32 v[80:81], 0
	v_mov_b64_e32 v[82:83], 0
	v_mov_b64_e32 v[84:85], 0
	v_mov_b64_e32 v[86:87], 0
	v_mov_b64_e32 v[88:89], 0
	v_mov_b64_e32 v[90:91], 0
	v_mov_b64_e32 v[92:93], 0
	v_mov_b64_e32 v[94:95], 0
	v_mov_b64_e32 v[96:97], 0
	v_mov_b64_e32 v[98:99], 0
	v_mov_b64_e32 v[100:101], 0
	v_mov_b64_e32 v[102:103], 0
	v_mov_b64_e32 v[104:105], 0
	v_mov_b64_e32 v[106:107], 0
	v_mov_b64_e32 v[108:109], 0
	v_mov_b64_e32 v[114:115], 0
	v_mov_b64_e32 v[116:117], 0
	v_mov_b64_e32 v[118:119], 0
	v_mov_b64_e32 v[120:121], 0
	v_mov_b64_e32 v[122:123], 0
	v_mov_b64_e32 v[124:125], 0
	s_waitcnt vmcnt(3)
	v_mov_b32_e32 v134, v2
	s_waitcnt vmcnt(0)
	v_mov_b32_e32 v135, v2
	v_mov_b32_e32 v136, v2
	v_mov_b32_e32 v137, v2
	v_mov_b32_e32 v138, v2
	v_mov_b32_e32 v139, v2
	v_mov_b32_e32 v140, v2
	v_mov_b32_e32 v141, v2

; template <class Epi, class Sched, bool ALIGN_EPI>
; __device__ __forceinline__ void gemm_phase(LAS unsigned char* lds, const Gemm g, const Sched& S, const Epi& E) {
;     ...
;         const bool has_next = S.next(ui + 1, nxt);
;         const char* nA = has_next ? (const char*)g.A + (size_t)nxt.pm * tstepA + (size_t)nxt.pn * g.a_koff * 2 : cA; const char* nB = has_next ? (const char*)g.Bt + (size_t)nxt.pn * tstepB : cB;
; #pragma unroll 1
;         for (int t = 0; t < nt; t += 2) {
;             const bool last = (t == nt - 2);
;             const char* a1 = cA + (size_t)(t + 1) * kstep;
;             const char* a2 = last ? nA : cA + (size_t)(t + 2) * kstep; const char* b2 = last ? nB : cB + (size_t)(t + 2) * kstep;
;             const char* a3 = a2 + kstep; const char* b3 = b2 + kstep;
;             PG8_LDB(B0, 0, 0); PG8_LDB(B1, 0, 1); PG8_SCHED; PG8_LDA(At, 0, 0); PG8_STAGE(PG8_SA(1, 1), a1 + hstepA, voffA);
;             PG8_WAIT_V(8); PG8_WAIT_L(0); PG8_BAR; PG8_MMA(0, 0, At, B0); PG8_MMA(0, 1, At, B1); PG8_BAR; PG8_SCHED;
;             PG8_LDA(At, 0, 1); PG8_STAGE(PG8_SB(0, 0), b2, voffB); PG8_STAGE(PG8_SB(0, 1), b2 + hstepB, voffB); PG8_STAGE(PG8_SA(0, 0), a2, voffA);
;             PG8_WAIT_V(8); PG8_WAIT_L(0); PG8_BAR; PG8_MMA(1, 0, At, B0); PG8_MMA(1, 1, At, B1); PG8_BAR; PG8_SCHED;
;             PG8_LDB(B0, 1, 0); PG8_LDB(B1, 1, 1); PG8_SCHED; PG8_LDA(At, 1, 0); PG8_STAGE(PG8_SA(0, 1), a2 + hstepA, voffA);
;             PG8_WAIT_V(8); PG8_WAIT_L(0); PG8_BAR; PG8_MMA(0, 0, At, B0); PG8_MMA(0, 1, At, B1); PG8_BAR; PG8_SCHED;
;             PG8_LDA(At, 1, 1); PG8_STAGE(PG8_SB(1, 0), b3, voffB); PG8_STAGE(PG8_SB(1, 1), b3 + hstepB, voffB); PG8_STAGE(PG8_SA(1, 0), a3, voffA);
;             PG8_WAIT_V(8); PG8_WAIT_L(0); PG8_BAR; PG8_MMA(1, 0, At, B0); PG8_MMA(1, 1, At, B1); PG8_BAR; PG8_SCHED;
;         }
;         if constexpr (ALIGN_EPI) { if (wr == 0) PG8_BAR; }
;         if constexpr (Epi::NPRE > 0) E(acc, cur, wr, wc, fr, fq, pre); else
;         if constexpr (!Epi::AFTER_DRAIN) E(acc, cur, wr, wc, fr, fq);
;         if (!has_next) break;
; #pragma unroll
;         for (int a = 0; a < 2; ++a)
; #pragma unroll
;             for (int b = 0; b < 2; ++b)
; #pragma unroll
;                 for (int m = 0; m < 4; ++m)
; #pragma unroll
;                     for (int n = 0; n < 2; ++n) acc[a][b][m][n] = (f32x4){0.f, 0.f, 0.f, 0.f};
.LBB0_1217:
	s_ashr_i32 s27, s26, 31
	s_lshl_b64 s[6:7], s[26:27], 20
	s_add_u32 s28, s23, s6
	s_addc_u32 s29, s24, s7
	s_and_b64 s[6:7], s[10:11], exec
	s_cselect_b32 s3, s29, s35
	s_cselect_b32 s5, s28, s34
	s_ashr_i32 s19, s18, 31
	s_lshl_b64 s[6:7], s[18:19], 20
	s_add_u32 s30, s25, s6
	s_addc_u32 s31, s44, s7
	s_and_b64 s[6:7], s[10:11], exec
	s_cselect_b32 s6, s31, s37
	s_cselect_b32 s7, s30, s36
	s_add_u32 s19, s36, 0x100
	v_mov_b32_e32 v2, 0
	s_addc_u32 s27, s37, 0
	s_mov_b32 s64, -2
	v_mov_b32_e32 v3, v2
	v_mov_b64_e32 v[4:5], 0
	v_mov_b64_e32 v[6:7], 0
	v_mov_b64_e32 v[8:9], 0
	v_mov_b64_e32 v[10:11], 0
	v_mov_b64_e32 v[12:13], 0
	v_mov_b64_e32 v[14:15], 0
	v_mov_b64_e32 v[16:17], 0
	v_mov_b64_e32 v[18:19], 0
	v_mov_b64_e32 v[20:21], 0
	v_mov_b64_e32 v[22:23], 0
	v_mov_b64_e32 v[24:25], 0
	v_mov_b64_e32 v[26:27], 0
	v_mov_b64_e32 v[28:29], 0
	v_mov_b64_e32 v[30:31], 0
	v_mov_b64_e32 v[32:33], 0
	v_mov_b64_e32 v[34:35], 0
	v_mov_b64_e32 v[36:37], 0
	v_mov_b64_e32 v[38:39], 0
	v_mov_b64_e32 v[40:41], 0
	v_mov_b64_e32 v[42:43], 0
	v_mov_b64_e32 v[44:45], 0
	v_mov_b64_e32 v[46:47], 0
	v_mov_b64_e32 v[48:49], 0
	v_mov_b64_e32 v[50:51], 0
	v_mov_b64_e32 v[52:53], 0
	v_mov_b64_e32 v[54:55], 0
	v_mov_b64_e32 v[56:57], 0
	v_mov_b64_e32 v[58:59], 0
	v_mov_b64_e32 v[60:61], 0
	v_mov_b64_e32 v[62:63], 0
	v_mov_b64_e32 v[64:65], 0
	v_mov_b64_e32 v[66:67], 0
	v_mov_b64_e32 v[68:69], 0
	v_mov_b64_e32 v[70:71], 0
	v_mov_b64_e32 v[72:73], 0
	v_mov_b64_e32 v[74:75], 0
	v_mov_b64_e32 v[76:77], 0
	v_mov_b64_e32 v[78:79], 0
	v_mov_b64_e32 v[80:81], 0
	v_mov_b64_e32 v[82:83], 0
	v_mov_b64_e32 v[84:85], 0
	v_mov_b64_e32 v[86:87], 0
	v_mov_b64_e32 v[88:89], 0
	v_mov_b64_e32 v[90:91], 0
	v_mov_b64_e32 v[92:93], 0
	v_mov_b64_e32 v[94:95], 0
	v_mov_b64_e32 v[96:97], 0
	v_mov_b64_e32 v[98:99], 0
	v_mov_b64_e32 v[100:101], 0
	v_mov_b64_e32 v[102:103], 0
	v_mov_b64_e32 v[104:105], 0
	v_mov_b64_e32 v[106:107], 0
	v_mov_b64_e32 v[108:109], 0
	v_mov_b64_e32 v[110:111], 0
	v_mov_b64_e32 v[112:113], 0
	v_mov_b64_e32 v[114:115], 0
	v_mov_b64_e32 v[116:117], 0
	v_mov_b64_e32 v[118:119], 0
	v_mov_b64_e32 v[120:121], 0
	v_mov_b64_e32 v[122:123], 0
	v_mov_b64_e32 v[124:125], 0
	v_mov_b64_e32 v[126:127], 0
	v_mov_b64_e32 v[128:129], 0

; template <class Epi, class Sched, bool ALIGN_EPI>
; __device__ __forceinline__ void gemm_phase(LAS unsigned char* lds, const Gemm g, const Sched& S, const Epi& E) {
;     ...
;     f32x4 acc[2][2][4][2];
; #pragma unroll
;     for (int a = 0; a < 2; ++a)
; #pragma unroll
;         for (int b = 0; b < 2; ++b)
; #pragma unroll
;             for (int m = 0; m < 4; ++m)
; #pragma unroll
;                 for (int n = 0; n < 2; ++n) acc[a][b][m][n] = (f32x4){0.f, 0.f, 0.f, 0.f};
;     ...
;             const char* a1 = cA + (size_t)(t + 1) * kstep;
;             const char* a2 = last ? nA : cA + (size_t)(t + 2) * kstep; const char* b2 = last ? nB : cB + (size_t)(t + 2) * kstep;
;             const char* a3 = a2 + kstep; const char* b3 = b2 + kstep;
.LBB0_1316:
	s_add_u32 s6, s28, 0x100
	s_addc_u32 s7, s29, 0
	s_add_u32 s56, s4, 0x100
	s_addc_u32 s57, s5, 0
	s_add_u32 s4, s28, 0x160080
	v_mov_b32_e32 v2, 0
	s_addc_u32 s5, s29, 0
	s_mov_b32 s58, -2
	s_waitcnt lgkmcnt(0)
	v_mov_b32_e32 v3, v2
	v_mov_b64_e32 v[4:5], 0
	v_mov_b64_e32 v[6:7], 0
	v_mov_b64_e32 v[8:9], 0
	v_mov_b64_e32 v[10:11], 0
	v_mov_b64_e32 v[12:13], 0
	v_mov_b64_e32 v[14:15], 0
	v_mov_b64_e32 v[16:17], 0
	v_mov_b64_e32 v[18:19], 0
	v_mov_b64_e32 v[20:21], 0
	v_mov_b64_e32 v[22:23], 0
	v_mov_b64_e32 v[24:25], 0
	v_mov_b64_e32 v[26:27], 0
	v_mov_b64_e32 v[28:29], 0
	v_mov_b64_e32 v[30:31], 0
	v_mov_b64_e32 v[32:33], 0
	v_mov_b64_e32 v[34:35], 0
	v_mov_b64_e32 v[36:37], 0
	v_mov_b64_e32 v[38:39], 0
	v_mov_b64_e32 v[40:41], 0
	v_mov_b64_e32 v[42:43], 0
	v_mov_b64_e32 v[44:45], 0
	v_mov_b64_e32 v[46:47], 0
	v_mov_b64_e32 v[48:49], 0
	v_mov_b64_e32 v[50:51], 0
	v_mov_b64_e32 v[52:53], 0
	v_mov_b64_e32 v[54:55], 0
	v_mov_b64_e32 v[56:57], 0
	v_mov_b64_e32 v[58:59], 0
	v_mov_b64_e32 v[60:61], 0
	v_mov_b64_e32 v[62:63], 0
	v_mov_b64_e32 v[64:65], 0
	v_mov_b64_e32 v[66:67], 0
	v_mov_b64_e32 v[68:69], 0
	v_mov_b64_e32 v[70:71], 0
	v_mov_b64_e32 v[72:73], 0
	v_mov_b64_e32 v[74:75], 0
	v_mov_b64_e32 v[76:77], 0
	v_mov_b64_e32 v[78:79], 0
	v_mov_b64_e32 v[80:81], 0
	v_mov_b64_e32 v[82:83], 0
	v_mov_b64_e32 v[84:85], 0
	v_mov_b64_e32 v[86:87], 0
	v_mov_b64_e32 v[88:89], 0
	v_mov_b64_e32 v[90:91], 0
	v_mov_b64_e32 v[92:93], 0
	v_mov_b64_e32 v[94:95], 0
	v_mov_b64_e32 v[96:97], 0
	v_mov_b64_e32 v[98:99], 0
	v_mov_b64_e32 v[100:101], 0
	v_mov_b64_e32 v[102:103], 0
	v_mov_b64_e32 v[104:105], 0
	v_mov_b64_e32 v[106:107], 0
	v_mov_b64_e32 v[108:109], 0
	v_mov_b64_e32 v[114:115], 0
	v_mov_b64_e32 v[116:117], 0
	v_mov_b64_e32 v[118:119], 0
	v_mov_b64_e32 v[120:121], 0
	v_mov_b64_e32 v[122:123], 0
	v_mov_b64_e32 v[124:125], 0
	s_waitcnt vmcnt(3)
	v_mov_b32_e32 v134, v2
	s_waitcnt vmcnt(0)
	v_mov_b32_e32 v135, v2
	v_mov_b32_e32 v136, v2
	v_mov_b32_e32 v137, v2
	v_mov_b32_e32 v138, v2
	v_mov_b32_e32 v139, v2
	v_mov_b32_e32 v140, v2
	v_mov_b32_e32 v141, v2

; template <class Epi, class Sched, bool ALIGN_EPI>
; __device__ __forceinline__ void gemm_phase(LAS unsigned char* lds, const Gemm g, const Sched& S, const Epi& E) {
;     ...
;         const bool has_next = S.next(ui + 1, nxt);
;         const char* nA = has_next ? (const char*)g.A + (size_t)nxt.pm * tstepA + (size_t)nxt.pn * g.a_koff * 2 : cA; const char* nB = has_next ? (const char*)g.Bt + (size_t)nxt.pn * tstepB : cB;
; #pragma unroll 1
;         for (int t = 0; t < nt; t += 2) {
;             const bool last = (t == nt - 2);
;             const char* a1 = cA + (size_t)(t + 1) * kstep;
;             const char* a2 = last ? nA : cA + (size_t)(t + 2) * kstep; const char* b2 = last ? nB : cB + (size_t)(t + 2) * kstep;
;             const char* a3 = a2 + kstep; const char* b3 = b2 + kstep;
;     ...
; #pragma unroll
;         for (int a = 0; a < 2; ++a)
; #pragma unroll
;             for (int b = 0; b < 2; ++b)
; #pragma unroll
;                 for (int m = 0; m < 4; ++m)
; #pragma unroll
;                     for (int n = 0; n < 2; ++n) acc[a][b][m][n] = (f32x4){0.f, 0.f, 0.f, 0.f};
;         cur = nxt; cA = nA; cB = nB; ++ui;
.LBB0_1408:
	s_mov_b32 s38, s6
	s_ashr_i32 s39, s6, 31
	s_mov_b32 s36, s2
	s_lshl_b64 s[2:3], s[38:39], 20
	s_add_u32 s40, s48, s2
	s_addc_u32 s41, s49, s3
	s_and_b64 s[2:3], s[44:45], exec
	s_cselect_b32 s2, s41, s5
	s_cselect_b32 s3, s40, s4
	s_ashr_i32 s37, s36, 31
	s_lshl_b64 s[6:7], s[36:37], 20
	s_add_u32 s42, s50, s6
	s_addc_u32 s43, s51, s7
	s_and_b64 s[6:7], s[44:45], exec
	s_cselect_b32 s6, s43, s9
	s_cselect_b32 s7, s42, s8
	s_add_u32 s23, s8, 0x100
	v_mov_b32_e32 v2, 0
	s_addc_u32 s37, s9, 0
	s_mov_b32 s39, -2
	v_mov_b32_e32 v3, v2
	v_mov_b64_e32 v[4:5], 0
	v_mov_b64_e32 v[6:7], 0
	v_mov_b64_e32 v[8:9], 0
	v_mov_b64_e32 v[10:11], 0
	v_mov_b64_e32 v[12:13], 0
	v_mov_b64_e32 v[14:15], 0
	v_mov_b64_e32 v[16:17], 0
	v_mov_b64_e32 v[18:19], 0
	v_mov_b64_e32 v[20:21], 0
	v_mov_b64_e32 v[22:23], 0
	v_mov_b64_e32 v[24:25], 0
	v_mov_b64_e32 v[26:27], 0
	v_mov_b64_e32 v[28:29], 0
	v_mov_b64_e32 v[30:31], 0
	v_mov_b64_e32 v[32:33], 0
	v_mov_b64_e32 v[34:35], 0
	v_mov_b64_e32 v[36:37], 0
	v_mov_b64_e32 v[38:39], 0
	v_mov_b64_e32 v[40:41], 0
	v_mov_b64_e32 v[42:43], 0
	v_mov_b64_e32 v[44:45], 0
	v_mov_b64_e32 v[46:47], 0
	v_mov_b64_e32 v[48:49], 0
	v_mov_b64_e32 v[50:51], 0
	v_mov_b64_e32 v[52:53], 0
	v_mov_b64_e32 v[54:55], 0
	v_mov_b64_e32 v[56:57], 0
	v_mov_b64_e32 v[58:59], 0
	v_mov_b64_e32 v[60:61], 0
	v_mov_b64_e32 v[62:63], 0
	v_mov_b64_e32 v[64:65], 0
	v_mov_b64_e32 v[66:67], 0
	v_mov_b64_e32 v[68:69], 0
	v_mov_b64_e32 v[70:71], 0
	v_mov_b64_e32 v[72:73], 0
	v_mov_b64_e32 v[74:75], 0
	v_mov_b64_e32 v[76:77], 0
	v_mov_b64_e32 v[78:79], 0
	v_mov_b64_e32 v[80:81], 0
	v_mov_b64_e32 v[82:83], 0
	v_mov_b64_e32 v[84:85], 0
	v_mov_b64_e32 v[86:87], 0
	v_mov_b64_e32 v[88:89], 0
	v_mov_b64_e32 v[90:91], 0
	v_mov_b64_e32 v[92:93], 0
	v_mov_b64_e32 v[94:95], 0
	v_mov_b64_e32 v[96:97], 0
	v_mov_b64_e32 v[98:99], 0
	v_mov_b64_e32 v[100:101], 0
	v_mov_b64_e32 v[102:103], 0
	v_mov_b64_e32 v[104:105], 0
	v_mov_b64_e32 v[106:107], 0
	v_mov_b64_e32 v[108:109], 0
	v_mov_b64_e32 v[110:111], 0
	v_mov_b64_e32 v[112:113], 0
	v_mov_b64_e32 v[114:115], 0
	v_mov_b64_e32 v[116:117], 0
	v_mov_b64_e32 v[118:119], 0
	v_mov_b64_e32 v[120:121], 0
	v_mov_b64_e32 v[122:123], 0
	v_mov_b64_e32 v[124:125], 0
	v_mov_b64_e32 v[126:127], 0
	v_mov_b64_e32 v[128:129], 0

; template <class Epi, class Sched, bool ALIGN_EPI>
; __device__ __forceinline__ void gemm_phase(LAS unsigned char* lds, const Gemm g, const Sched& S, const Epi& E) {
;     ...
;         const bool has_next = S.next(ui + 1, nxt);
;         const char* nA = has_next ? (const char*)g.A + (size_t)nxt.pm * tstepA + (size_t)nxt.pn * g.a_koff * 2 : cA; const char* nB = has_next ? (const char*)g.Bt + (size_t)nxt.pn * tstepB : cB;
; #pragma unroll 1
;         for (int t = 0; t < nt; t += 2) {
;             const bool last = (t == nt - 2);
;             const char* a1 = cA + (size_t)(t + 1) * kstep;
;             const char* a2 = last ? nA : cA + (size_t)(t + 2) * kstep; const char* b2 = last ? nB : cB + (size_t)(t + 2) * kstep;
;             const char* a3 = a2 + kstep; const char* b3 = b2 + kstep;
;     ...
; #pragma unroll
;         for (int a = 0; a < 2; ++a)
; #pragma unroll
;             for (int b = 0; b < 2; ++b)
; #pragma unroll
;                 for (int m = 0; m < 4; ++m)
; #pragma unroll
;                     for (int n = 0; n < 2; ++n) acc[a][b][m][n] = (f32x4){0.f, 0.f, 0.f, 0.f};
;         cur = nxt; cA = nA; cB = nB; ++ui;
.LBB0_1993:
	s_ashr_i32 s21, s20, 31
	s_lshl_b64 s[6:7], s[20:21], 20
	s_add_u32 s22, s36, s6
	s_addc_u32 s23, s37, s7
	s_and_b64 s[6:7], s[12:13], exec
	s_cselect_b32 s3, s23, s29
	s_cselect_b32 s5, s22, s28
	s_ashr_i32 s19, s18, 31
	s_lshl_b64 s[6:7], s[18:19], 20
	s_add_u32 s24, s38, s6
	s_addc_u32 s25, s39, s7
	s_and_b64 s[6:7], s[12:13], exec
	s_cselect_b32 s6, s25, s27
	s_cselect_b32 s7, s24, s26
	s_add_u32 s19, s28, 0x100
	s_addc_u32 s21, s29, 0
	s_add_u32 s57, s26, 0x100
	s_addc_u32 s58, s27, 0
	s_add_u32 s26, s28, 0x80080
	v_mov_b32_e32 v2, 0
	s_addc_u32 s27, s29, 0
	s_mov_b32 s59, -2
	s_waitcnt lgkmcnt(0)
	v_mov_b32_e32 v3, v2
	v_mov_b64_e32 v[4:5], 0
	v_mov_b64_e32 v[6:7], 0
	v_mov_b64_e32 v[8:9], 0
	v_mov_b64_e32 v[10:11], 0
	v_mov_b64_e32 v[12:13], 0
	v_mov_b64_e32 v[14:15], 0
	v_mov_b64_e32 v[16:17], 0
	v_mov_b64_e32 v[18:19], 0
	v_mov_b64_e32 v[20:21], 0
	v_mov_b64_e32 v[22:23], 0
	v_mov_b64_e32 v[24:25], 0
	v_mov_b64_e32 v[26:27], 0
	v_mov_b64_e32 v[28:29], 0
	v_mov_b64_e32 v[30:31], 0
	v_mov_b64_e32 v[32:33], 0
	v_mov_b64_e32 v[34:35], 0
	v_mov_b64_e32 v[36:37], 0
	v_mov_b64_e32 v[38:39], 0
	v_mov_b64_e32 v[40:41], 0
	v_mov_b64_e32 v[42:43], 0
	v_mov_b64_e32 v[44:45], 0
	v_mov_b64_e32 v[46:47], 0
	v_mov_b64_e32 v[48:49], 0
	v_mov_b64_e32 v[50:51], 0
	v_mov_b64_e32 v[52:53], 0
	v_mov_b64_e32 v[54:55], 0
	v_mov_b64_e32 v[56:57], 0
	v_mov_b64_e32 v[58:59], 0
	v_mov_b64_e32 v[60:61], 0
	v_mov_b64_e32 v[62:63], 0
	v_mov_b64_e32 v[64:65], 0
	v_mov_b64_e32 v[66:67], 0
	v_mov_b64_e32 v[68:69], 0
	v_mov_b64_e32 v[70:71], 0
	v_mov_b64_e32 v[72:73], 0
	v_mov_b64_e32 v[82:83], 0
	v_mov_b64_e32 v[84:85], 0
	v_mov_b64_e32 v[86:87], 0
	v_mov_b64_e32 v[88:89], 0
	s_waitcnt vmcnt(11)
	v_mov_b32_e32 v98, v2
	v_mov_b32_e32 v99, v2
	v_mov_b32_e32 v100, v2
	v_mov_b32_e32 v101, v2
	s_waitcnt vmcnt(10)
	v_mov_b32_e32 v102, v2
	v_mov_b32_e32 v103, v2
	v_mov_b32_e32 v104, v2
	v_mov_b32_e32 v105, v2
	s_waitcnt vmcnt(6)
	v_mov_b32_e32 v118, v2
	v_mov_b32_e32 v119, v2
	v_mov_b32_e32 v120, v2
	v_mov_b32_e32 v121, v2
	s_waitcnt vmcnt(5)
	v_mov_b32_e32 v122, v2
	v_mov_b32_e32 v123, v2
	v_mov_b32_e32 v124, v2
	v_mov_b32_e32 v125, v2
	v_mov_b32_e32 v74, v2
	v_mov_b32_e32 v75, v2
	v_mov_b32_e32 v76, v2
	v_mov_b32_e32 v77, v2
	v_mov_b32_e32 v78, v2
	v_mov_b32_e32 v79, v2
	v_mov_b32_e32 v80, v2
	v_mov_b32_e32 v81, v2
	v_mov_b32_e32 v90, v2
	v_mov_b32_e32 v91, v2
	v_mov_b32_e32 v92, v2
	v_mov_b32_e32 v93, v2
	v_mov_b32_e32 v94, v2
	v_mov_b32_e32 v95, v2
	v_mov_b32_e32 v96, v2
	v_mov_b32_e32 v97, v2
	v_mov_b32_e32 v106, v2
	v_mov_b32_e32 v107, v2
	v_mov_b32_e32 v108, v2
	v_mov_b32_e32 v109, v2
	v_mov_b32_e32 v114, v2
	v_mov_b32_e32 v115, v2
	v_mov_b32_e32 v116, v2
	v_mov_b32_e32 v117, v2
	s_waitcnt vmcnt(2)
	v_mov_b32_e32 v134, v2
	s_waitcnt vmcnt(0)
	v_mov_b32_e32 v135, v2
	v_mov_b32_e32 v136, v2
	v_mov_b32_e32 v137, v2
	v_mov_b32_e32 v138, v2
	v_mov_b32_e32 v139, v2
	v_mov_b32_e32 v140, v2
	v_mov_b32_e32 v141, v2

; template <class Epi, class Sched, bool ALIGN_EPI>
; __device__ __forceinline__ void gemm_phase(LAS unsigned char* lds, const Gemm g, const Sched& S, const Epi& E) {
;     ...
;         const bool has_next = S.next(ui + 1, nxt);
;         const char* nA = has_next ? (const char*)g.A + (size_t)nxt.pm * tstepA + (size_t)nxt.pn * g.a_koff * 2 : cA; const char* nB = has_next ? (const char*)g.Bt + (size_t)nxt.pn * tstepB : cB;
; #pragma unroll 1
;         for (int t = 0; t < nt; t += 2) {
;             const bool last = (t == nt - 2);
;             const char* a1 = cA + (size_t)(t + 1) * kstep;
;             const char* a2 = last ? nA : cA + (size_t)(t + 2) * kstep; const char* b2 = last ? nB : cB + (size_t)(t + 2) * kstep;
;             const char* a3 = a2 + kstep; const char* b3 = b2 + kstep;
;     ...
; #pragma unroll
;         for (int a = 0; a < 2; ++a)
; #pragma unroll
;             for (int b = 0; b < 2; ++b)
; #pragma unroll
;                 for (int m = 0; m < 4; ++m)
; #pragma unroll
;                     for (int n = 0; n < 2; ++n) acc[a][b][m][n] = (f32x4){0.f, 0.f, 0.f, 0.f};
;         cur = nxt; cA = nA; cB = nB; ++ui;
.LBB0_2074:
	s_ashr_i32 s21, s20, 31
	s_lshl_b64 s[6:7], s[20:21], 20
	s_add_u32 s22, s38, s6
	s_addc_u32 s23, s39, s7
	s_and_b64 s[6:7], s[10:11], exec
	s_cselect_b32 s3, s23, s27
	s_cselect_b32 s5, s22, s26
	s_ashr_i32 s19, s18, 31
	s_lshl_b64 s[6:7], s[18:19], 20
	s_add_u32 s24, s40, s6
	s_addc_u32 s25, s41, s7
	s_and_b64 s[6:7], s[10:11], exec
	s_cselect_b32 s6, s25, s29
	s_cselect_b32 s7, s24, s28
	s_add_u32 s19, s28, 0x100
	v_mov_b32_e32 v2, 0
	s_addc_u32 s21, s29, 0
	s_mov_b32 s60, -2
	v_mov_b32_e32 v3, v2
	v_mov_b64_e32 v[4:5], 0
	v_mov_b64_e32 v[6:7], 0
	v_mov_b64_e32 v[8:9], 0
	v_mov_b64_e32 v[10:11], 0
	v_mov_b64_e32 v[12:13], 0
	v_mov_b64_e32 v[14:15], 0
	v_mov_b64_e32 v[16:17], 0
	v_mov_b64_e32 v[18:19], 0
	v_mov_b64_e32 v[20:21], 0
	v_mov_b64_e32 v[22:23], 0
	v_mov_b64_e32 v[24:25], 0
	v_mov_b64_e32 v[26:27], 0
	v_mov_b64_e32 v[28:29], 0
	v_mov_b64_e32 v[30:31], 0
	v_mov_b64_e32 v[32:33], 0
	v_mov_b64_e32 v[34:35], 0
	v_mov_b64_e32 v[36:37], 0
	v_mov_b64_e32 v[38:39], 0
	v_mov_b64_e32 v[40:41], 0
	v_mov_b64_e32 v[42:43], 0
	v_mov_b64_e32 v[44:45], 0
	v_mov_b64_e32 v[46:47], 0
	v_mov_b64_e32 v[48:49], 0
	v_mov_b64_e32 v[50:51], 0
	v_mov_b64_e32 v[52:53], 0
	v_mov_b64_e32 v[54:55], 0
	v_mov_b64_e32 v[56:57], 0
	v_mov_b64_e32 v[58:59], 0
	v_mov_b64_e32 v[60:61], 0
	v_mov_b64_e32 v[62:63], 0
	v_mov_b64_e32 v[64:65], 0
	v_mov_b64_e32 v[66:67], 0
	v_mov_b64_e32 v[68:69], 0
	v_mov_b64_e32 v[70:71], 0
	v_mov_b64_e32 v[72:73], 0
	v_mov_b64_e32 v[74:75], 0
	v_mov_b64_e32 v[76:77], 0
	v_mov_b64_e32 v[78:79], 0
	v_mov_b64_e32 v[80:81], 0
	v_mov_b64_e32 v[82:83], 0
	v_mov_b64_e32 v[84:85], 0
	v_mov_b64_e32 v[86:87], 0
	v_mov_b64_e32 v[88:89], 0
	v_mov_b64_e32 v[90:91], 0
	v_mov_b64_e32 v[92:93], 0
	v_mov_b64_e32 v[94:95], 0
	v_mov_b64_e32 v[96:97], 0
	v_mov_b64_e32 v[98:99], 0
	v_mov_b64_e32 v[100:101], 0
	v_mov_b64_e32 v[102:103], 0
	v_mov_b64_e32 v[104:105], 0
	v_mov_b64_e32 v[106:107], 0
	v_mov_b64_e32 v[108:109], 0
	v_mov_b64_e32 v[110:111], 0
	v_mov_b64_e32 v[112:113], 0
	v_mov_b64_e32 v[114:115], 0
	v_mov_b64_e32 v[116:117], 0
	v_mov_b64_e32 v[118:119], 0
	v_mov_b64_e32 v[120:121], 0
	v_mov_b64_e32 v[122:123], 0
	v_mov_b64_e32 v[124:125], 0
	v_mov_b64_e32 v[126:127], 0
	v_mov_b64_e32 v[128:129], 0

; #define PG8_STAGE(bufoff, gbase, voff) do { _Pragma("unroll") for (int _i = 0; _i < 2; ++_i) { unsigned keep_; \
;         asm volatile("s_mov_b32 %0, m0\n\ts_mov_b32 m0, %3\n\ts_nop 0\n\tglobal_load_lds_dwordx4 %1, %2\n\ts_mov_b32 m0, %0" \
;             : "=&s"(keep_) : "v"((voff)[_i]), "s"((const void*)(gbase)), "s"(ldsb0 + (unsigned)(bufoff) + (unsigned)(_i * 8192)) : "memory"); } } while (0)
; #define PG8_LDA(dst, b, h) do { _Pragma("unroll") for (int m = 0; m < 4; ++m) _Pragma("unroll") for (int k = 0; k < 2; ++k) dst[m][k] = *(const LAS bf16x8*)(lds + PG8_SA(b, h) + aoff + m * 2048 + k * 1024); } while (0)
; #define PG8_LDB(dst, b, h) do { _Pragma("unroll") for (int n = 0; n < 2; ++n) _Pragma("unroll") for (int k = 0; k < 2; ++k) dst[n][k] = *(const LAS bf16x8*)(lds + PG8_SB(b, h) + boff + n * 2048 + k * 1024); } while (0)
; #define PG8_MMA(ai, bj, At, Bt) do { __builtin_amdgcn_s_setprio(1); _Pragma("unroll") for (int m = 0; m < 4; ++m) _Pragma("unroll") for (int n = 0; n < 2; ++n) _Pragma("unroll") for (int k = 0; k < 2; ++k) \
;         acc[ai][bj][m][n] = __builtin_amdgcn_mfma_f32_16x16x32_bf16(Bt[n][k], At[m][k], acc[ai][bj][m][n], 0, 0, 0); __builtin_amdgcn_s_setprio(0); } while (0)
; #define PG8_WAIT_V(n) asm volatile("s_waitcnt vmcnt(" #n ")" ::: "memory")
; #define PG8_BAR __builtin_amdgcn_s_barrier()
; template <class Epi, class Sched, bool ALIGN_EPI>
; __device__ __forceinline__ void gemm_phase(LAS unsigned char* lds, const Gemm g, const Sched& S, const Epi& E) {
;     ...
;         for (int t = 0; t < nt; t += 2) {
;             const bool last = (t == nt - 2);
;             const char* a1 = cA + (size_t)(t + 1) * kstep;
;             const char* a2 = last ? nA : cA + (size_t)(t + 2) * kstep; const char* b2 = last ? nB : cB + (size_t)(t + 2) * kstep;
;             const char* a3 = a2 + kstep; const char* b3 = b2 + kstep;
;             PG8_LDB(B0, 0, 0); PG8_LDB(B1, 0, 1); PG8_SCHED; PG8_LDA(At, 0, 0); PG8_STAGE(PG8_SA(1, 1), a1 + hstepA, voffA);
;             PG8_WAIT_V(8); PG8_WAIT_L(0); PG8_BAR; PG8_MMA(0, 0, At, B0); PG8_MMA(0, 1, At, B1); PG8_BAR; PG8_SCHED;
;             PG8_LDA(At, 0, 1); PG8_STAGE(PG8_SB(0, 0), b2, voffB); PG8_STAGE(PG8_SB(0, 1), b2 + hstepB, voffB); PG8_STAGE(PG8_SA(0, 0), a2, voffA);
;             PG8_WAIT_V(8); PG8_WAIT_L(0); PG8_BAR; PG8_MMA(1, 0, At, B0); PG8_MMA(1, 1, At, B1); PG8_BAR; PG8_SCHED;
.LBB0_2172:
	s_add_u32 s61, s22, s26
	s_addc_u32 s63, s23, s27
	s_add_u32 s28, s61, 0x100
	v_add_u32_e32 v141, 0x10000, v139
	s_addc_u32 s29, s63, 0
	ds_read_b128 v[142:145], v141
	ds_read_b128 v[146:149], v141 offset:1024
	ds_read_b128 v[150:153], v141 offset:2048
	ds_read_b128 v[154:157], v141 offset:3072
	v_add_u32_e32 v141, 0x14000, v139
	s_add_u32 s30, s20, s26
	ds_read_b128 v[158:161], v141
	ds_read_b128 v[162:165], v141 offset:1024
	ds_read_b128 v[166:169], v141 offset:2048
	ds_read_b128 v[170:173], v141 offset:3072
	s_addc_u32 s31, s21, s27
	s_add_u32 s30, s30, 0x100
	s_addc_u32 s31, s31, 0
	s_cmpk_eq_i32 s60, 0x54
	s_cselect_b32 s34, s12, s28
	s_cselect_b32 s35, s13, s29
	s_cselect_b32 s30, s24, s30
	s_cselect_b32 s31, s25, s31
	s_add_u32 s28, s34, 0x80
	s_addc_u32 s29, s35, 0
	ds_read_b128 v[174:177], v140
	ds_read_b128 v[178:181], v140 offset:1024
	ds_read_b128 v[182:185], v140 offset:2048
	ds_read_b128 v[186:189], v140 offset:3072
	ds_read_b128 v[190:193], v140 offset:4096
	ds_read_b128 v[194:197], v140 offset:5120
	ds_read_b128 v[198:201], v140 offset:6144
	ds_read_b128 v[204:207], v140 offset:7168
	s_add_u32 s62, s61, 0x160080
	s_addc_u32 s63, s63, 0
	s_mov_b32 m0, s54
	s_nop 0
	global_load_lds_dwordx4 v131, s[62:63]
	s_nop 0
	s_mov_b32 m0, s55
	s_nop 0
	global_load_lds_dwordx4 v137, s[62:63]
	s_waitcnt vmcnt(8)
	s_waitcnt lgkmcnt(0)
	s_barrier
	s_setprio 1
	v_mfma_f32_16x16x32_bf16 v[126:129], v[142:145], v[174:177], v[126:129]
	v_mfma_f32_16x16x32_bf16 v[122:125], v[150:153], v[174:177], v[122:125]
	v_mfma_f32_16x16x32_bf16 v[110:113], v[142:145], v[182:185], v[110:113]
	v_mfma_f32_16x16x32_bf16 v[106:109], v[150:153], v[182:185], v[106:109]
	v_mfma_f32_16x16x32_bf16 v[94:97], v[142:145], v[190:193], v[94:97]
	v_mfma_f32_16x16x32_bf16 v[90:93], v[150:153], v[190:193], v[90:93]
	v_mfma_f32_16x16x32_bf16 v[78:81], v[142:145], v[198:201], v[78:81]
	v_mfma_f32_16x16x32_bf16 v[74:77], v[150:153], v[198:201], v[74:77]
	v_mfma_f32_16x16x32_bf16 v[126:129], v[146:149], v[178:181], v[126:129]
	v_mfma_f32_16x16x32_bf16 v[122:125], v[154:157], v[178:181], v[122:125]
	v_mfma_f32_16x16x32_bf16 v[110:113], v[146:149], v[186:189], v[110:113]
	v_mfma_f32_16x16x32_bf16 v[106:109], v[154:157], v[186:189], v[106:109]
	v_mfma_f32_16x16x32_bf16 v[94:97], v[146:149], v[194:197], v[94:97]
	v_mfma_f32_16x16x32_bf16 v[90:93], v[154:157], v[194:197], v[90:93]
	v_mfma_f32_16x16x32_bf16 v[78:81], v[146:149], v[204:207], v[78:81]
	v_mfma_f32_16x16x32_bf16 v[74:77], v[154:157], v[204:207], v[74:77]
	v_mfma_f32_16x16x32_bf16 v[118:121], v[158:161], v[174:177], v[118:121]
	v_mfma_f32_16x16x32_bf16 v[114:117], v[166:169], v[174:177], v[114:117]
	v_mfma_f32_16x16x32_bf16 v[102:105], v[158:161], v[182:185], v[102:105]
	v_mfma_f32_16x16x32_bf16 v[98:101], v[166:169], v[182:185], v[98:101]
	v_mfma_f32_16x16x32_bf16 v[86:89], v[158:161], v[190:193], v[86:89]
	v_mfma_f32_16x16x32_bf16 v[82:85], v[166:169], v[190:193], v[82:85]
	v_mfma_f32_16x16x32_bf16 v[70:73], v[158:161], v[198:201], v[70:73]
	v_mfma_f32_16x16x32_bf16 v[66:69], v[166:169], v[198:201], v[66:69]
	v_mfma_f32_16x16x32_bf16 v[118:121], v[162:165], v[178:181], v[118:121]
	v_mfma_f32_16x16x32_bf16 v[114:117], v[170:173], v[178:181], v[114:117]
	v_mfma_f32_16x16x32_bf16 v[102:105], v[162:165], v[186:189], v[102:105]
	v_mfma_f32_16x16x32_bf16 v[98:101], v[170:173], v[186:189], v[98:101]
	v_mfma_f32_16x16x32_bf16 v[86:89], v[162:165], v[194:197], v[86:89]
	v_mfma_f32_16x16x32_bf16 v[82:85], v[170:173], v[194:197], v[82:85]
	v_mfma_f32_16x16x32_bf16 v[70:73], v[162:165], v[204:207], v[70:73]
	v_mfma_f32_16x16x32_bf16 v[66:69], v[170:173], v[204:207], v[66:69]
	s_setprio 0
	s_barrier
	ds_read_b128 v[174:177], v140 offset:16384
	ds_read_b128 v[178:181], v140 offset:17408
	ds_read_b128 v[182:185], v140 offset:18432
	ds_read_b128 v[186:189], v140 offset:19456
	ds_read_b128 v[190:193], v140 offset:20480
	ds_read_b128 v[194:197], v140 offset:21504
	ds_read_b128 v[198:201], v140 offset:22528
	ds_read_b128 v[204:207], v140 offset:23552
	s_mov_b32 m0, s3
	s_nop 0
	global_load_lds_dwordx4 v136, s[30:31]
	s_add_u32 s62, s30, 0x160000
	s_mov_b32 m0, s41
	s_nop 0
	global_load_lds_dwordx4 v138, s[30:31]
	s_addc_u32 s63, s31, 0
	s_mov_b32 m0, s42
	s_nop 0
	global_load_lds_dwordx4 v136, s[62:63]
	s_nop 0
	s_mov_b32 m0, s43
	s_nop 0
	global_load_lds_dwordx4 v138, s[62:63]
	s_nop 0
	s_mov_b32 m0, s2
	s_nop 0
	global_load_lds_dwordx4 v131, s[34:35]
	s_nop 0
	s_mov_b32 m0, s44
	s_nop 0
	global_load_lds_dwordx4 v137, s[34:35]
	s_waitcnt vmcnt(8)
	s_waitcnt lgkmcnt(0)
	s_barrier
; #define PG8_STAGE(bufoff, gbase, voff) do { _Pragma("unroll") for (int _i = 0; _i < 2; ++_i) { unsigned keep_; \
;         asm volatile("s_mov_b32 %0, m0\n\ts_mov_b32 m0, %3\n\ts_nop 0\n\tglobal_load_lds_dwordx4 %1, %2\n\ts_mov_b32 m0, %0" \
;             : "=&s"(keep_) : "v"((voff)[_i]), "s"((const void*)(gbase)), "s"(ldsb0 + (unsigned)(bufoff) + (unsigned)(_i * 8192)) : "memory"); } } while (0)
; #define PG8_LDA(dst, b, h) do { _Pragma("unroll") for (int m = 0; m < 4; ++m) _Pragma("unroll") for (int k = 0; k < 2; ++k) dst[m][k] = *(const LAS bf16x8*)(lds + PG8_SA(b, h) + aoff + m * 2048 + k * 1024); } while (0)
; #define PG8_LDB(dst, b, h) do { _Pragma("unroll") for (int n = 0; n < 2; ++n) _Pragma("unroll") for (int k = 0; k < 2; ++k) dst[n][k] = *(const LAS bf16x8*)(lds + PG8_SB(b, h) + boff + n * 2048 + k * 1024); } while (0)
; #define PG8_MMA(ai, bj, At, Bt) do { __builtin_amdgcn_s_setprio(1); _Pragma("unroll") for (int m = 0; m < 4; ++m) _Pragma("unroll") for (int n = 0; n < 2; ++n) _Pragma("unroll") for (int k = 0; k < 2; ++k) \
;         acc[ai][bj][m][n] = __builtin_amdgcn_mfma_f32_16x16x32_bf16(Bt[n][k], At[m][k], acc[ai][bj][m][n], 0, 0, 0); __builtin_amdgcn_s_setprio(0); } while (0)
; #define PG8_WAIT_V(n) asm volatile("s_waitcnt vmcnt(" #n ")" ::: "memory")
; #define PG8_WAIT_L(n) asm volatile("s_waitcnt lgkmcnt(" #n ")" ::: "memory")
; #define PG8_BAR __builtin_amdgcn_s_barrier()
; #define PG8_SCHED __builtin_amdgcn_sched_barrier(0)
; template <class Epi, class Sched, bool ALIGN_EPI>
; __device__ __forceinline__ void gemm_phase(LAS unsigned char* lds, const Gemm g, const Sched& S, const Epi& E) {
;     ...
;             PG8_WAIT_V(8); PG8_WAIT_L(0); PG8_BAR; PG8_MMA(1, 0, At, B0); PG8_MMA(1, 1, At, B1); PG8_BAR; PG8_SCHED;
;             PG8_LDB(B0, 1, 0); PG8_LDB(B1, 1, 1); PG8_SCHED; PG8_LDA(At, 1, 0); PG8_STAGE(PG8_SA(0, 1), a2 + hstepA, voffA);
;             PG8_WAIT_V(8); PG8_WAIT_L(0); PG8_BAR; PG8_MMA(0, 0, At, B0); PG8_MMA(0, 1, At, B1); PG8_BAR; PG8_SCHED;
	s_setprio 1
	v_mfma_f32_16x16x32_bf16 v[62:65], v[142:145], v[174:177], v[62:65]
	v_mfma_f32_16x16x32_bf16 v[58:61], v[150:153], v[174:177], v[58:61]
	v_mfma_f32_16x16x32_bf16 v[46:49], v[142:145], v[182:185], v[46:49]
	v_mfma_f32_16x16x32_bf16 v[42:45], v[150:153], v[182:185], v[42:45]
	v_mfma_f32_16x16x32_bf16 v[30:33], v[142:145], v[190:193], v[30:33]
	v_mfma_f32_16x16x32_bf16 v[26:29], v[150:153], v[190:193], v[26:29]
	v_mfma_f32_16x16x32_bf16 v[14:17], v[142:145], v[198:201], v[14:17]
	v_mfma_f32_16x16x32_bf16 v[10:13], v[150:153], v[198:201], v[10:13]
	v_mfma_f32_16x16x32_bf16 v[62:65], v[146:149], v[178:181], v[62:65]
	v_mfma_f32_16x16x32_bf16 v[58:61], v[154:157], v[178:181], v[58:61]
	v_mfma_f32_16x16x32_bf16 v[46:49], v[146:149], v[186:189], v[46:49]
	v_mfma_f32_16x16x32_bf16 v[42:45], v[154:157], v[186:189], v[42:45]
	v_mfma_f32_16x16x32_bf16 v[30:33], v[146:149], v[194:197], v[30:33]
	v_mfma_f32_16x16x32_bf16 v[26:29], v[154:157], v[194:197], v[26:29]
	v_mfma_f32_16x16x32_bf16 v[14:17], v[146:149], v[204:207], v[14:17]
	v_mfma_f32_16x16x32_bf16 v[10:13], v[154:157], v[204:207], v[10:13]
	v_mfma_f32_16x16x32_bf16 v[54:57], v[158:161], v[174:177], v[54:57]
	v_mfma_f32_16x16x32_bf16 v[50:53], v[166:169], v[174:177], v[50:53]
	v_mfma_f32_16x16x32_bf16 v[38:41], v[158:161], v[182:185], v[38:41]
	v_mfma_f32_16x16x32_bf16 v[34:37], v[166:169], v[182:185], v[34:37]
	v_mfma_f32_16x16x32_bf16 v[22:25], v[158:161], v[190:193], v[22:25]
	v_mfma_f32_16x16x32_bf16 v[18:21], v[166:169], v[190:193], v[18:21]
	v_mfma_f32_16x16x32_bf16 v[6:9], v[158:161], v[198:201], v[6:9]
	v_mfma_f32_16x16x32_bf16 v[2:5], v[166:169], v[198:201], v[2:5]
	v_mfma_f32_16x16x32_bf16 v[54:57], v[162:165], v[178:181], v[54:57]
	v_mfma_f32_16x16x32_bf16 v[50:53], v[170:173], v[178:181], v[50:53]
	v_mfma_f32_16x16x32_bf16 v[38:41], v[162:165], v[186:189], v[38:41]
	v_mfma_f32_16x16x32_bf16 v[34:37], v[170:173], v[186:189], v[34:37]
	v_mfma_f32_16x16x32_bf16 v[22:25], v[162:165], v[194:197], v[22:25]
	v_mfma_f32_16x16x32_bf16 v[18:21], v[170:173], v[194:197], v[18:21]
	v_mfma_f32_16x16x32_bf16 v[6:9], v[162:165], v[204:207], v[6:9]
	v_mfma_f32_16x16x32_bf16 v[2:5], v[170:173], v[204:207], v[2:5]
	s_setprio 0
	s_barrier
	v_add_u32_e32 v141, 0x18000, v139
	ds_read_b128 v[142:145], v141
	ds_read_b128 v[146:149], v141 offset:1024
	ds_read_b128 v[150:153], v141 offset:2048
	ds_read_b128 v[154:157], v141 offset:3072
	v_add_u32_e32 v141, 0x1c000, v139
	ds_read_b128 v[158:161], v141
	ds_read_b128 v[162:165], v141 offset:1024
	ds_read_b128 v[166:169], v141 offset:2048
	ds_read_b128 v[170:173], v141 offset:3072
	ds_read_b128 v[174:177], v140 offset:32768
	ds_read_b128 v[178:181], v140 offset:33792
	ds_read_b128 v[182:185], v140 offset:34816
	ds_read_b128 v[186:189], v140 offset:35840
	ds_read_b128 v[190:193], v140 offset:36864
	ds_read_b128 v[194:197], v140 offset:37888
	ds_read_b128 v[198:201], v140 offset:38912
	ds_read_b128 v[204:207], v140 offset:39936
	s_add_u32 s34, s34, 0x160000
	s_addc_u32 s35, s35, 0
	s_mov_b32 m0, s46
	s_nop 0
	global_load_lds_dwordx4 v131, s[34:35]
	s_nop 0
	s_mov_b32 m0, s47
	s_nop 0
	global_load_lds_dwordx4 v137, s[34:35]
	s_waitcnt vmcnt(8)
	s_waitcnt lgkmcnt(0)
	s_barrier
	s_setprio 1
	v_mfma_f32_16x16x32_bf16 v[126:129], v[142:145], v[174:177], v[126:129]
	v_mfma_f32_16x16x32_bf16 v[122:125], v[150:153], v[174:177], v[122:125]
	v_mfma_f32_16x16x32_bf16 v[110:113], v[142:145], v[182:185], v[110:113]
	v_mfma_f32_16x16x32_bf16 v[106:109], v[150:153], v[182:185], v[106:109]
	v_mfma_f32_16x16x32_bf16 v[94:97], v[142:145], v[190:193], v[94:97]
	v_mfma_f32_16x16x32_bf16 v[90:93], v[150:153], v[190:193], v[90:93]
	v_mfma_f32_16x16x32_bf16 v[78:81], v[142:145], v[198:201], v[78:81]
	v_mfma_f32_16x16x32_bf16 v[74:77], v[150:153], v[198:201], v[74:77]
	v_mfma_f32_16x16x32_bf16 v[126:129], v[146:149], v[178:181], v[126:129]
	v_mfma_f32_16x16x32_bf16 v[122:125], v[154:157], v[178:181], v[122:125]
	v_mfma_f32_16x16x32_bf16 v[110:113], v[146:149], v[186:189], v[110:113]
	v_mfma_f32_16x16x32_bf16 v[106:109], v[154:157], v[186:189], v[106:109]
	v_mfma_f32_16x16x32_bf16 v[94:97], v[146:149], v[194:197], v[94:97]
	v_mfma_f32_16x16x32_bf16 v[90:93], v[154:157], v[194:197], v[90:93]
	v_mfma_f32_16x16x32_bf16 v[78:81], v[146:149], v[204:207], v[78:81]
	v_mfma_f32_16x16x32_bf16 v[74:77], v[154:157], v[204:207], v[74:77]
	v_mfma_f32_16x16x32_bf16 v[118:121], v[158:161], v[174:177], v[118:121]
	v_mfma_f32_16x16x32_bf16 v[114:117], v[166:169], v[174:177], v[114:117]
	v_mfma_f32_16x16x32_bf16 v[102:105], v[158:161], v[182:185], v[102:105]
	v_mfma_f32_16x16x32_bf16 v[98:101], v[166:169], v[182:185], v[98:101]
	v_mfma_f32_16x16x32_bf16 v[86:89], v[158:161], v[190:193], v[86:89]
	v_mfma_f32_16x16x32_bf16 v[82:85], v[166:169], v[190:193], v[82:85]
	v_mfma_f32_16x16x32_bf16 v[70:73], v[158:161], v[198:201], v[70:73]
	v_mfma_f32_16x16x32_bf16 v[66:69], v[166:169], v[198:201], v[66:69]
	v_mfma_f32_16x16x32_bf16 v[118:121], v[162:165], v[178:181], v[118:121]
	v_mfma_f32_16x16x32_bf16 v[114:117], v[170:173], v[178:181], v[114:117]
	v_mfma_f32_16x16x32_bf16 v[102:105], v[162:165], v[186:189], v[102:105]
	v_mfma_f32_16x16x32_bf16 v[98:101], v[170:173], v[186:189], v[98:101]
	v_mfma_f32_16x16x32_bf16 v[86:89], v[162:165], v[194:197], v[86:89]
	v_mfma_f32_16x16x32_bf16 v[82:85], v[170:173], v[194:197], v[82:85]
	v_mfma_f32_16x16x32_bf16 v[70:73], v[162:165], v[204:207], v[70:73]
	v_mfma_f32_16x16x32_bf16 v[66:69], v[170:173], v[204:207], v[66:69]
	s_setprio 0
	s_barrier
; #define PG8_STAGE(bufoff, gbase, voff) do { _Pragma("unroll") for (int _i = 0; _i < 2; ++_i) { unsigned keep_; \
;         asm volatile("s_mov_b32 %0, m0\n\ts_mov_b32 m0, %3\n\ts_nop 0\n\tglobal_load_lds_dwordx4 %1, %2\n\ts_mov_b32 m0, %0" \
;             : "=&s"(keep_) : "v"((voff)[_i]), "s"((const void*)(gbase)), "s"(ldsb0 + (unsigned)(bufoff) + (unsigned)(_i * 8192)) : "memory"); } } while (0)
; #define PG8_LDA(dst, b, h) do { _Pragma("unroll") for (int m = 0; m < 4; ++m) _Pragma("unroll") for (int k = 0; k < 2; ++k) dst[m][k] = *(const LAS bf16x8*)(lds + PG8_SA(b, h) + aoff + m * 2048 + k * 1024); } while (0)
; #define PG8_MMA(ai, bj, At, Bt) do { __builtin_amdgcn_s_setprio(1); _Pragma("unroll") for (int m = 0; m < 4; ++m) _Pragma("unroll") for (int n = 0; n < 2; ++n) _Pragma("unroll") for (int k = 0; k < 2; ++k) \
;         acc[ai][bj][m][n] = __builtin_amdgcn_mfma_f32_16x16x32_bf16(Bt[n][k], At[m][k], acc[ai][bj][m][n], 0, 0, 0); __builtin_amdgcn_s_setprio(0); } while (0)
; #define PG8_WAIT_V(n) asm volatile("s_waitcnt vmcnt(" #n ")" ::: "memory")
; #define PG8_WAIT_L(n) asm volatile("s_waitcnt lgkmcnt(" #n ")" ::: "memory")
; #define PG8_BAR __builtin_amdgcn_s_barrier()
; #define PG8_SCHED __builtin_amdgcn_sched_barrier(0)
; template <class Epi, class Sched, bool ALIGN_EPI>
; __device__ __forceinline__ void gemm_phase(LAS unsigned char* lds, const Gemm g, const Sched& S, const Epi& E) {
;     ...
;             PG8_LDA(At, 1, 1); PG8_STAGE(PG8_SB(1, 0), b3, voffB); PG8_STAGE(PG8_SB(1, 1), b3 + hstepB, voffB); PG8_STAGE(PG8_SA(1, 0), a3, voffA);
;             PG8_WAIT_V(8); PG8_WAIT_L(0); PG8_BAR; PG8_MMA(1, 0, At, B0); PG8_MMA(1, 1, At, B1); PG8_BAR; PG8_SCHED;
;         }
;         if constexpr (ALIGN_EPI) { if (wr == 0) PG8_BAR; }
;         if constexpr (Epi::NPRE > 0) E(acc, cur, wr, wc, fr, fq, pre); else
;         if constexpr (!Epi::AFTER_DRAIN) E(acc, cur, wr, wc, fr, fq);
;         if (!has_next) break;
; #pragma unroll
;         for (int a = 0; a < 2; ++a)
; #pragma unroll
;             for (int b = 0; b < 2; ++b)
; #pragma unroll
;                 for (int m = 0; m < 4; ++m)
; #pragma unroll
;                     for (int n = 0; n < 2; ++n) acc[a][b][m][n] = (f32x4){0.f, 0.f, 0.f, 0.f};
;         cur = nxt; cA = nA; cB = nB; ++ui;
	ds_read_b128 v[174:177], v140 offset:49152
	ds_read_b128 v[178:181], v140 offset:50176
	ds_read_b128 v[182:185], v140 offset:51200
	ds_read_b128 v[186:189], v140 offset:52224
	ds_read_b128 v[190:193], v140 offset:53248
	ds_read_b128 v[194:197], v140 offset:54272
	ds_read_b128 v[198:201], v140 offset:55296
	ds_read_b128 v[204:207], v140 offset:56320
	s_add_u32 s34, s30, 0x80
	s_addc_u32 s35, s31, 0
	s_mov_b32 m0, s48
	s_nop 0
	global_load_lds_dwordx4 v136, s[34:35]
	s_add_u32 s30, s30, 0x160080
	s_mov_b32 m0, s49
	s_nop 0
	global_load_lds_dwordx4 v138, s[34:35]
	s_addc_u32 s31, s31, 0
	s_mov_b32 m0, s52
	s_nop 0
	global_load_lds_dwordx4 v136, s[30:31]
	s_nop 0
	s_mov_b32 m0, s53
	s_nop 0
	global_load_lds_dwordx4 v138, s[30:31]
	s_mov_b32 m0, s50
	s_nop 0
	global_load_lds_dwordx4 v131, s[28:29]
	s_nop 0
	s_mov_b32 m0, s51
	s_nop 0
	global_load_lds_dwordx4 v137, s[28:29]
	s_waitcnt vmcnt(8)
	s_waitcnt lgkmcnt(0)
	s_barrier
	s_setprio 1
	v_mfma_f32_16x16x32_bf16 v[62:65], v[142:145], v[174:177], v[62:65]
	v_mfma_f32_16x16x32_bf16 v[58:61], v[150:153], v[174:177], v[58:61]
	v_mfma_f32_16x16x32_bf16 v[46:49], v[142:145], v[182:185], v[46:49]
	v_mfma_f32_16x16x32_bf16 v[42:45], v[150:153], v[182:185], v[42:45]
	v_mfma_f32_16x16x32_bf16 v[30:33], v[142:145], v[190:193], v[30:33]
	v_mfma_f32_16x16x32_bf16 v[26:29], v[150:153], v[190:193], v[26:29]
	v_mfma_f32_16x16x32_bf16 v[14:17], v[142:145], v[198:201], v[14:17]
	v_mfma_f32_16x16x32_bf16 v[10:13], v[150:153], v[198:201], v[10:13]
	v_mfma_f32_16x16x32_bf16 v[62:65], v[146:149], v[178:181], v[62:65]
	v_mfma_f32_16x16x32_bf16 v[58:61], v[154:157], v[178:181], v[58:61]
	v_mfma_f32_16x16x32_bf16 v[46:49], v[146:149], v[186:189], v[46:49]
	v_mfma_f32_16x16x32_bf16 v[42:45], v[154:157], v[186:189], v[42:45]
	v_mfma_f32_16x16x32_bf16 v[30:33], v[146:149], v[194:197], v[30:33]
	v_mfma_f32_16x16x32_bf16 v[26:29], v[154:157], v[194:197], v[26:29]
	v_mfma_f32_16x16x32_bf16 v[14:17], v[146:149], v[204:207], v[14:17]
	v_mfma_f32_16x16x32_bf16 v[10:13], v[154:157], v[204:207], v[10:13]
	v_mfma_f32_16x16x32_bf16 v[54:57], v[158:161], v[174:177], v[54:57]
	v_mfma_f32_16x16x32_bf16 v[50:53], v[166:169], v[174:177], v[50:53]
	v_mfma_f32_16x16x32_bf16 v[38:41], v[158:161], v[182:185], v[38:41]
	v_mfma_f32_16x16x32_bf16 v[34:37], v[166:169], v[182:185], v[34:37]
	v_mfma_f32_16x16x32_bf16 v[22:25], v[158:161], v[190:193], v[22:25]
	v_mfma_f32_16x16x32_bf16 v[18:21], v[166:169], v[190:193], v[18:21]
	v_mfma_f32_16x16x32_bf16 v[6:9], v[158:161], v[198:201], v[6:9]
	v_mfma_f32_16x16x32_bf16 v[2:5], v[166:169], v[198:201], v[2:5]
	v_mfma_f32_16x16x32_bf16 v[54:57], v[162:165], v[178:181], v[54:57]
	v_mfma_f32_16x16x32_bf16 v[50:53], v[170:173], v[178:181], v[50:53]
	v_mfma_f32_16x16x32_bf16 v[38:41], v[162:165], v[186:189], v[38:41]
	v_mfma_f32_16x16x32_bf16 v[34:37], v[170:173], v[186:189], v[34:37]
	v_mfma_f32_16x16x32_bf16 v[22:25], v[162:165], v[194:197], v[22:25]
	v_mfma_f32_16x16x32_bf16 v[18:21], v[170:173], v[194:197], v[18:21]
	v_mfma_f32_16x16x32_bf16 v[6:9], v[162:165], v[204:207], v[6:9]
	v_mfma_f32_16x16x32_bf16 v[2:5], v[170:173], v[204:207], v[2:5]
	s_setprio 0
	s_barrier
	s_add_i32 s60, s60, 2
	s_add_u32 s26, s26, 0x100
	s_addc_u32 s27, s27, 0
	s_cmpk_gt_u32 s60, 0x55
	s_cbranch_scc0 .LBB0_2172
	s_and_b64 vcc, exec, s[10:11]
	s_cbranch_vccnz .LBB0_2160
	v_mov_b32_e32 v2, 0
	s_mov_b32 s45, s57
	s_mov_b32 s17, s58
	s_mov_b64 s[20:21], s[24:25]
	s_mov_b64 s[22:23], s[12:13]
	s_mov_b32 s56, s59
	v_mov_b32_e32 v3, v2
	v_mov_b64_e32 v[4:5], 0
	v_mov_b64_e32 v[6:7], 0
	v_mov_b64_e32 v[8:9], 0
	v_mov_b64_e32 v[10:11], 0
	v_mov_b64_e32 v[12:13], 0
	v_mov_b64_e32 v[14:15], 0
	v_mov_b64_e32 v[16:17], 0
	v_mov_b64_e32 v[18:19], 0
	v_mov_b64_e32 v[20:21], 0
	v_mov_b64_e32 v[22:23], 0
	v_mov_b64_e32 v[24:25], 0
	v_mov_b64_e32 v[26:27], 0
	v_mov_b64_e32 v[28:29], 0
	v_mov_b64_e32 v[30:31], 0
	v_mov_b64_e32 v[32:33], 0
	v_mov_b64_e32 v[34:35], 0
	v_mov_b64_e32 v[36:37], 0
	v_mov_b64_e32 v[38:39], 0
	v_mov_b64_e32 v[40:41], 0
	v_mov_b64_e32 v[42:43], 0
	v_mov_b64_e32 v[44:45], 0
	v_mov_b64_e32 v[46:47], 0
	v_mov_b64_e32 v[48:49], 0
	v_mov_b64_e32 v[50:51], 0
	v_mov_b64_e32 v[52:53], 0
	v_mov_b64_e32 v[54:55], 0
	v_mov_b64_e32 v[56:57], 0
	v_mov_b64_e32 v[58:59], 0
	v_mov_b64_e32 v[60:61], 0
	v_mov_b64_e32 v[62:63], 0
	v_mov_b64_e32 v[64:65], 0
	v_mov_b64_e32 v[66:67], 0
	v_mov_b64_e32 v[68:69], 0
	v_mov_b64_e32 v[70:71], 0
	v_mov_b64_e32 v[72:73], 0
	v_mov_b64_e32 v[74:75], 0
	v_mov_b64_e32 v[76:77], 0
	v_mov_b64_e32 v[78:79], 0
	v_mov_b64_e32 v[80:81], 0
	v_mov_b64_e32 v[82:83], 0
	v_mov_b64_e32 v[84:85], 0
	v_mov_b64_e32 v[86:87], 0
	v_mov_b64_e32 v[88:89], 0
	v_mov_b64_e32 v[90:91], 0
	v_mov_b64_e32 v[92:93], 0
	v_mov_b64_e32 v[94:95], 0
	v_mov_b64_e32 v[96:97], 0
	v_mov_b64_e32 v[98:99], 0
	v_mov_b64_e32 v[100:101], 0
	v_mov_b64_e32 v[102:103], 0
	v_mov_b64_e32 v[104:105], 0
	v_mov_b64_e32 v[106:107], 0
	v_mov_b64_e32 v[108:109], 0
	v_mov_b64_e32 v[110:111], 0
	v_mov_b64_e32 v[112:113], 0
	v_mov_b64_e32 v[114:115], 0
	v_mov_b64_e32 v[116:117], 0
	v_mov_b64_e32 v[118:119], 0
	v_mov_b64_e32 v[120:121], 0
	v_mov_b64_e32 v[122:123], 0
	v_mov_b64_e32 v[124:125], 0
	v_mov_b64_e32 v[126:127], 0
	v_mov_b64_e32 v[128:129], 0
	s_branch .LBB0_2160
